# residual GEMM epilogue: the four X quarter-row loads of each row group issued together with counted waits (stores counted as younger)
# speedup vs baseline: 1.0084x; 1.0084x over previous
; #define PG8_STAGE(bufoff, gbase, voff) do { _Pragma("unroll") for (int _i = 0; _i < 2; ++_i) \
;         __builtin_amdgcn_global_load_lds((const unsigned*)((const char*)(gbase) + (voff)[_i]), (LAS unsigned*)(lds + (bufoff) + ldsw + _i * 8192), 16, 0, 0); } while (0)
; #define PG8_LDA(dst, b, h) do { _Pragma("unroll") for (int m = 0; m < 4; ++m) _Pragma("unroll") for (int k = 0; k < 2; ++k) dst[m][k] = *(const LAS bf16x8*)(lds + PG8_SA(b, h) + aoff + m * 2048 + k * 1024); } while (0)
; #define PG8_LDB(dst, b, h) do { _Pragma("unroll") for (int n = 0; n < 2; ++n) _Pragma("unroll") for (int k = 0; k < 2; ++k) dst[n][k] = *(const LAS bf16x8*)(lds + PG8_SB(b, h) + boff + n * 2048 + k * 1024); } while (0)
; #define PG8_MMA(ai, bj, At, Bt) do { __builtin_amdgcn_s_setprio(1); _Pragma("unroll") for (int m = 0; m < 4; ++m) _Pragma("unroll") for (int n = 0; n < 2; ++n) _Pragma("unroll") for (int k = 0; k < 2; ++k) \
;         acc[ai][bj][m][n] = __builtin_amdgcn_mfma_f32_16x16x32_bf16(Bt[n][k], At[m][k], acc[ai][bj][m][n], 0, 0, 0); __builtin_amdgcn_s_setprio(0); } while (0)
; #define PG8_WAIT_L(n) asm volatile("s_waitcnt lgkmcnt(" #n ")" ::: "memory")
; #define PG8_BAR __builtin_amdgcn_s_barrier()
; #define PG8_SCHED __builtin_amdgcn_sched_barrier(0)
; template <class Epi>
; __device__ __forceinline__ void gemm_phase(LAS unsigned char* lds, const Gemm g, const StaticOrder& S, const Epi& E) {
;     ...
;         for (int t = 0; t < nt; t += 2) {
;             const bool last = (t == nt - 2);
;             const char* a1 = cA + (size_t)(t + 1) * kstep;
;             const char* a2 = last ? nA : cA + (size_t)(t + 2) * kstep; const char* b2 = last ? nB : cB + (size_t)(t + 2) * kstep;
;             const char* a3 = a2 + kstep; const char* b3 = b2 + kstep;
;             PG8_LDB(B0, 0, 0); PG8_SCHED; PG8_LDA(At, 0, 0); PG8_STAGE(PG8_SA(1, 1), a1 + hstep, voffA);
;             PG8_WAIT_L(8); PG8_BAR; PG8_WAIT_L(0); PG8_MMA(0, 0, At, B0); PG8_BAR; PG8_SCHED;
;             PG8_LDB(B1, 0, 1); PG8_STAGE(PG8_SB(0, 0), b2, voffB);
;             PG8_BAR; PG8_WAIT_L(0); PG8_MMA(0, 1, At, B1); PG8_BAR;
;             PG8_LDA(At, 0, 1); PG8_STAGE(PG8_SA(0, 0), a2, voffA);
;             PG8_BAR; PG8_WAIT_L(0); PG8_MMA(1, 0, At, B0); PG8_BAR; PG8_SCHED;
.LBB0_674:
	s_add_i32 s7, s6, 2
	s_add_u32 s8, s44, 0x80
	s_addc_u32 s9, s45, 0
	s_add_i32 s10, 0, 0x10000
	v_add_u32_e32 v145, s10, v142
	ds_read_b128 v[138:141], v145
	ds_read_b128 v[146:149], v145 offset:1024
	ds_read_b128 v[150:153], v145 offset:2048
	ds_read_b128 v[156:159], v145 offset:3072
	s_cmp_eq_u32 s64, s6
	s_cselect_b32 s47, s27, s9
	s_cselect_b32 s46, s26, s8
	s_cselect_b32 s49, s39, s5
	s_cselect_b32 s48, s38, s4
	v_lshl_add_u64 v[192:193], s[44:45], 0, v[134:135]
	s_add_i32 m0, s56, 0xc000
	ds_read_b128 v[160:163], v144
	ds_read_b128 v[164:167], v144 offset:1024
	ds_read_b128 v[168:171], v144 offset:2048
	ds_read_b128 v[172:175], v144 offset:3072
	ds_read_b128 v[176:179], v144 offset:4096
	ds_read_b128 v[180:183], v144 offset:5120
	ds_read_b128 v[184:187], v144 offset:6144
	ds_read_b128 v[188:191], v144 offset:7168
	global_load_lds_dwordx4 v[192:193], off
	v_lshl_add_u64 v[192:193], s[44:45], 0, v[136:137]
	s_add_i32 m0, s56, 0xe000
	s_nop 0
	global_load_lds_dwordx4 v[192:193], off
	s_waitcnt lgkmcnt(8)
	s_barrier
	s_waitcnt lgkmcnt(0)
	s_setprio 1
	s_waitcnt lgkmcnt(0)
	v_mfma_f32_16x16x32_bf16 v[126:129], v[138:141], v[160:163], v[126:129]
	v_mfma_f32_16x16x32_bf16 v[122:125], v[150:153], v[160:163], v[122:125]
	v_mfma_f32_16x16x32_bf16 v[110:113], v[138:141], v[168:171], v[110:113]
	v_mfma_f32_16x16x32_bf16 v[106:109], v[150:153], v[168:171], v[106:109]
	v_mfma_f32_16x16x32_bf16 v[94:97], v[138:141], v[176:179], v[94:97]
	v_mfma_f32_16x16x32_bf16 v[90:93], v[150:153], v[176:179], v[90:93]
	v_mfma_f32_16x16x32_bf16 v[78:81], v[138:141], v[184:187], v[78:81]
	v_mfma_f32_16x16x32_bf16 v[74:77], v[150:153], v[184:187], v[74:77]
	v_mfma_f32_16x16x32_bf16 v[126:129], v[146:149], v[164:167], v[126:129]
	v_mfma_f32_16x16x32_bf16 v[122:125], v[156:159], v[164:167], v[122:125]
	v_mfma_f32_16x16x32_bf16 v[110:113], v[146:149], v[172:175], v[110:113]
	v_mfma_f32_16x16x32_bf16 v[106:109], v[156:159], v[172:175], v[106:109]
	v_mfma_f32_16x16x32_bf16 v[94:97], v[146:149], v[180:183], v[94:97]
	v_mfma_f32_16x16x32_bf16 v[90:93], v[156:159], v[180:183], v[90:93]
	v_mfma_f32_16x16x32_bf16 v[78:81], v[146:149], v[188:191], v[78:81]
	v_mfma_f32_16x16x32_bf16 v[74:77], v[156:159], v[188:191], v[74:77]
	s_setprio 0
	s_barrier
	s_add_i32 s6, 0, 0x14000
	s_add_i32 s8, s10, s55
	v_add_u32_e32 v145, s6, v142
	v_lshl_add_u64 v[206:207], s[48:49], 0, v[130:131]
	s_mov_b32 m0, s8
	ds_read_b128 v[192:195], v145
	ds_read_b128 v[224:227], v145 offset:1024
	ds_read_b128 v[228:231], v145 offset:2048
	ds_read_b128 v[232:235], v145 offset:3072
	global_load_lds_dwordx4 v[206:207], off
	v_lshl_add_u64 v[208:209], s[48:49], 0, v[132:133]
	s_add_i32 m0, s8, 0x2000
	s_nop 0
	global_load_lds_dwordx4 v[208:209], off
	s_barrier
	s_waitcnt lgkmcnt(0)
	s_setprio 1
	s_waitcnt lgkmcnt(0)
	v_mfma_f32_16x16x32_bf16 v[118:121], v[192:195], v[160:163], v[118:121]
	v_mfma_f32_16x16x32_bf16 v[114:117], v[228:231], v[160:163], v[114:117]
	v_mfma_f32_16x16x32_bf16 v[102:105], v[192:195], v[168:171], v[102:105]
	v_mfma_f32_16x16x32_bf16 v[98:101], v[228:231], v[168:171], v[98:101]
	v_mfma_f32_16x16x32_bf16 v[86:89], v[192:195], v[176:179], v[86:89]
	v_mfma_f32_16x16x32_bf16 v[82:85], v[228:231], v[176:179], v[82:85]
	v_mfma_f32_16x16x32_bf16 v[70:73], v[192:195], v[184:187], v[70:73]
	v_mfma_f32_16x16x32_bf16 v[66:69], v[228:231], v[184:187], v[66:69]
	v_mfma_f32_16x16x32_bf16 v[118:121], v[224:227], v[164:167], v[118:121]
	v_mfma_f32_16x16x32_bf16 v[114:117], v[232:235], v[164:167], v[114:117]
	v_mfma_f32_16x16x32_bf16 v[102:105], v[224:227], v[172:175], v[102:105]
	v_mfma_f32_16x16x32_bf16 v[98:101], v[232:235], v[172:175], v[98:101]
	v_mfma_f32_16x16x32_bf16 v[86:89], v[224:227], v[180:183], v[86:89]
	v_mfma_f32_16x16x32_bf16 v[82:85], v[232:235], v[180:183], v[82:85]
	v_mfma_f32_16x16x32_bf16 v[70:73], v[224:227], v[188:191], v[70:73]
	v_mfma_f32_16x16x32_bf16 v[66:69], v[232:235], v[188:191], v[66:69]
	s_setprio 0
	s_mov_b32 m0, s56
	v_lshl_add_u64 v[210:211], s[46:47], 0, v[130:131]
	s_barrier
	ds_read_b128 v[160:163], v144 offset:16384
	ds_read_b128 v[164:167], v144 offset:17408
	ds_read_b128 v[168:171], v144 offset:18432
	ds_read_b128 v[172:175], v144 offset:19456
	ds_read_b128 v[176:179], v144 offset:20480
	ds_read_b128 v[180:183], v144 offset:21504
	ds_read_b128 v[184:187], v144 offset:22528
	ds_read_b128 v[188:191], v144 offset:23552
	global_load_lds_dwordx4 v[210:211], off
	v_lshl_add_u64 v[212:213], s[46:47], 0, v[132:133]
	s_mov_b32 m0, s57
	s_nop 0
	global_load_lds_dwordx4 v[212:213], off
	s_barrier
	s_waitcnt lgkmcnt(0)
	s_setprio 1
	s_waitcnt lgkmcnt(0)
	v_mfma_f32_16x16x32_bf16 v[62:65], v[138:141], v[160:163], v[62:65]
	v_mfma_f32_16x16x32_bf16 v[58:61], v[150:153], v[160:163], v[58:61]
	v_mfma_f32_16x16x32_bf16 v[46:49], v[138:141], v[168:171], v[46:49]
	v_mfma_f32_16x16x32_bf16 v[42:45], v[150:153], v[168:171], v[42:45]
	v_mfma_f32_16x16x32_bf16 v[30:33], v[138:141], v[176:179], v[30:33]
	v_mfma_f32_16x16x32_bf16 v[26:29], v[150:153], v[176:179], v[26:29]
	v_mfma_f32_16x16x32_bf16 v[14:17], v[138:141], v[184:187], v[14:17]
	v_mfma_f32_16x16x32_bf16 v[10:13], v[150:153], v[184:187], v[10:13]
	v_mfma_f32_16x16x32_bf16 v[62:65], v[146:149], v[164:167], v[62:65]
	v_mfma_f32_16x16x32_bf16 v[58:61], v[156:159], v[164:167], v[58:61]
	v_mfma_f32_16x16x32_bf16 v[46:49], v[146:149], v[172:175], v[46:49]
	v_mfma_f32_16x16x32_bf16 v[42:45], v[156:159], v[172:175], v[42:45]
	v_mfma_f32_16x16x32_bf16 v[30:33], v[146:149], v[180:183], v[30:33]
	v_mfma_f32_16x16x32_bf16 v[26:29], v[156:159], v[180:183], v[26:29]
	v_mfma_f32_16x16x32_bf16 v[14:17], v[146:149], v[188:191], v[14:17]
	v_mfma_f32_16x16x32_bf16 v[10:13], v[156:159], v[188:191], v[10:13]
	s_setprio 0
	s_barrier
; #define PG8_STAGE(bufoff, gbase, voff) do { _Pragma("unroll") for (int _i = 0; _i < 2; ++_i) \
;         __builtin_amdgcn_global_load_lds((const unsigned*)((const char*)(gbase) + (voff)[_i]), (LAS unsigned*)(lds + (bufoff) + ldsw + _i * 8192), 16, 0, 0); } while (0)
; #define PG8_LDA(dst, b, h) do { _Pragma("unroll") for (int m = 0; m < 4; ++m) _Pragma("unroll") for (int k = 0; k < 2; ++k) dst[m][k] = *(const LAS bf16x8*)(lds + PG8_SA(b, h) + aoff + m * 2048 + k * 1024); } while (0)
; #define PG8_LDB(dst, b, h) do { _Pragma("unroll") for (int n = 0; n < 2; ++n) _Pragma("unroll") for (int k = 0; k < 2; ++k) dst[n][k] = *(const LAS bf16x8*)(lds + PG8_SB(b, h) + boff + n * 2048 + k * 1024); } while (0)
; #define PG8_MMA(ai, bj, At, Bt) do { __builtin_amdgcn_s_setprio(1); _Pragma("unroll") for (int m = 0; m < 4; ++m) _Pragma("unroll") for (int n = 0; n < 2; ++n) _Pragma("unroll") for (int k = 0; k < 2; ++k) \
;         acc[ai][bj][m][n] = __builtin_amdgcn_mfma_f32_16x16x32_bf16(Bt[n][k], At[m][k], acc[ai][bj][m][n], 0, 0, 0); __builtin_amdgcn_s_setprio(0); } while (0)
; #define PG8_WAIT_V(n) asm volatile("s_waitcnt vmcnt(" #n ")" ::: "memory")
; #define PG8_WAIT_L(n) asm volatile("s_waitcnt lgkmcnt(" #n ")" ::: "memory")
; #define PG8_BAR __builtin_amdgcn_s_barrier()
; #define PG8_SCHED __builtin_amdgcn_sched_barrier(0)
; template <class Epi>
; __device__ __forceinline__ void gemm_phase(LAS unsigned char* lds, const Gemm g, const StaticOrder& S, const Epi& E) {
;     ...
;             PG8_STAGE(PG8_SB(0, 1), b2 + hstep, voffB);
;             PG8_WAIT_V(6); PG8_BAR; PG8_MMA(1, 1, At, B1); PG8_BAR;
;             PG8_LDB(B0, 1, 0); PG8_SCHED; PG8_LDA(At, 1, 0); PG8_STAGE(PG8_SA(0, 1), a2 + hstep, voffA);
;             PG8_WAIT_L(8); PG8_BAR; PG8_WAIT_L(0); PG8_MMA(0, 0, At, B0); PG8_BAR; PG8_SCHED;
;             PG8_LDB(B1, 1, 1); PG8_STAGE(PG8_SB(1, 0), b3, voffB);
;             PG8_BAR; PG8_WAIT_L(0); PG8_MMA(0, 1, At, B1); PG8_BAR;
;             PG8_LDA(At, 1, 1); PG8_STAGE(PG8_SA(1, 0), a3, voffA);
;             PG8_BAR; PG8_WAIT_L(0); PG8_MMA(1, 0, At, B0); PG8_BAR; PG8_SCHED;
	s_add_u32 s8, s48, s20
	s_addc_u32 s9, s49, 0
	s_add_i32 s6, s6, s55
	v_lshl_add_u64 v[214:215], s[8:9], 0, v[130:131]
	s_mov_b32 m0, s6
	v_lshl_add_u64 v[216:217], s[8:9], 0, v[132:133]
	global_load_lds_dwordx4 v[214:215], off
	s_add_i32 m0, s6, 0x2000
	s_nop 0
	global_load_lds_dwordx4 v[216:217], off
	s_waitcnt vmcnt(6)
	s_barrier
	s_setprio 1
	v_mfma_f32_16x16x32_bf16 v[54:57], v[192:195], v[160:163], v[54:57]
	v_mfma_f32_16x16x32_bf16 v[50:53], v[228:231], v[160:163], v[50:53]
	v_mfma_f32_16x16x32_bf16 v[38:41], v[192:195], v[168:171], v[38:41]
	v_mfma_f32_16x16x32_bf16 v[34:37], v[228:231], v[168:171], v[34:37]
	v_mfma_f32_16x16x32_bf16 v[22:25], v[192:195], v[176:179], v[22:25]
	v_mfma_f32_16x16x32_bf16 v[18:21], v[228:231], v[176:179], v[18:21]
	v_mfma_f32_16x16x32_bf16 v[6:9], v[192:195], v[184:187], v[6:9]
	v_mfma_f32_16x16x32_bf16 v[2:5], v[228:231], v[184:187], v[2:5]
	v_mfma_f32_16x16x32_bf16 v[54:57], v[224:227], v[164:167], v[54:57]
	v_mfma_f32_16x16x32_bf16 v[50:53], v[232:235], v[164:167], v[50:53]
	v_mfma_f32_16x16x32_bf16 v[38:41], v[224:227], v[172:175], v[38:41]
	v_mfma_f32_16x16x32_bf16 v[34:37], v[232:235], v[172:175], v[34:37]
	v_mfma_f32_16x16x32_bf16 v[22:25], v[224:227], v[180:183], v[22:25]
	v_mfma_f32_16x16x32_bf16 v[18:21], v[232:235], v[180:183], v[18:21]
	v_mfma_f32_16x16x32_bf16 v[6:9], v[224:227], v[188:191], v[6:9]
	v_mfma_f32_16x16x32_bf16 v[2:5], v[232:235], v[188:191], v[2:5]
	s_setprio 0
	s_add_i32 s6, 0, 0x18000
	v_add_u32_e32 v145, s6, v142
	s_barrier
	ds_read_b128 v[138:141], v145
	ds_read_b128 v[146:149], v145 offset:1024
	ds_read_b128 v[150:153], v145 offset:2048
	ds_read_b128 v[156:159], v145 offset:3072
	s_add_u32 s8, s46, s20
	s_addc_u32 s9, s47, 0
	s_mov_b32 m0, s58
	v_lshl_add_u64 v[192:193], s[8:9], 0, v[130:131]
	ds_read_b128 v[160:163], v144 offset:32768
	ds_read_b128 v[164:167], v144 offset:33792
	ds_read_b128 v[168:171], v144 offset:34816
	ds_read_b128 v[172:175], v144 offset:35840
	ds_read_b128 v[176:179], v144 offset:36864
	ds_read_b128 v[180:183], v144 offset:37888
	ds_read_b128 v[184:187], v144 offset:38912
	ds_read_b128 v[188:191], v144 offset:39936
	global_load_lds_dwordx4 v[192:193], off
	v_lshl_add_u64 v[192:193], s[8:9], 0, v[132:133]
	s_mov_b32 m0, s59
	s_nop 0
	global_load_lds_dwordx4 v[192:193], off
	s_waitcnt lgkmcnt(8)
	s_barrier
	s_waitcnt lgkmcnt(0)
	s_setprio 1
	s_waitcnt lgkmcnt(0)
	v_mfma_f32_16x16x32_bf16 v[126:129], v[138:141], v[160:163], v[126:129]
	v_mfma_f32_16x16x32_bf16 v[122:125], v[150:153], v[160:163], v[122:125]
	v_mfma_f32_16x16x32_bf16 v[110:113], v[138:141], v[168:171], v[110:113]
	v_mfma_f32_16x16x32_bf16 v[106:109], v[150:153], v[168:171], v[106:109]
	v_mfma_f32_16x16x32_bf16 v[94:97], v[138:141], v[176:179], v[94:97]
	v_mfma_f32_16x16x32_bf16 v[90:93], v[150:153], v[176:179], v[90:93]
	v_mfma_f32_16x16x32_bf16 v[78:81], v[138:141], v[184:187], v[78:81]
	v_mfma_f32_16x16x32_bf16 v[74:77], v[150:153], v[184:187], v[74:77]
	v_mfma_f32_16x16x32_bf16 v[126:129], v[146:149], v[164:167], v[126:129]
	v_mfma_f32_16x16x32_bf16 v[122:125], v[156:159], v[164:167], v[122:125]
	v_mfma_f32_16x16x32_bf16 v[110:113], v[146:149], v[172:175], v[110:113]
	v_mfma_f32_16x16x32_bf16 v[106:109], v[156:159], v[172:175], v[106:109]
	v_mfma_f32_16x16x32_bf16 v[94:97], v[146:149], v[180:183], v[94:97]
	v_mfma_f32_16x16x32_bf16 v[90:93], v[156:159], v[180:183], v[90:93]
	v_mfma_f32_16x16x32_bf16 v[78:81], v[146:149], v[188:191], v[78:81]
	v_mfma_f32_16x16x32_bf16 v[74:77], v[156:159], v[188:191], v[74:77]
	s_setprio 0
	s_barrier
	s_add_i32 s8, 0, 0x1c000
	s_add_i32 s6, s6, s55
	v_add_u32_e32 v145, s8, v142
	v_lshl_add_u64 v[206:207], v[206:207], 0, s[36:37]
	s_mov_b32 m0, s6
	ds_read_b128 v[192:195], v145
	ds_read_b128 v[224:227], v145 offset:1024
	ds_read_b128 v[228:231], v145 offset:2048
	ds_read_b128 v[232:235], v145 offset:3072
	global_load_lds_dwordx4 v[206:207], off
	v_lshl_add_u64 v[206:207], v[208:209], 0, s[36:37]
	s_add_i32 m0, s6, 0x2000
	s_nop 0
	global_load_lds_dwordx4 v[206:207], off
	s_barrier
	s_waitcnt lgkmcnt(0)
	s_setprio 1
	s_waitcnt lgkmcnt(0)
	v_mfma_f32_16x16x32_bf16 v[118:121], v[192:195], v[160:163], v[118:121]
	v_mfma_f32_16x16x32_bf16 v[114:117], v[228:231], v[160:163], v[114:117]
	v_mfma_f32_16x16x32_bf16 v[102:105], v[192:195], v[168:171], v[102:105]
	v_mfma_f32_16x16x32_bf16 v[98:101], v[228:231], v[168:171], v[98:101]
	v_mfma_f32_16x16x32_bf16 v[86:89], v[192:195], v[176:179], v[86:89]
	v_mfma_f32_16x16x32_bf16 v[82:85], v[228:231], v[176:179], v[82:85]
	v_mfma_f32_16x16x32_bf16 v[70:73], v[192:195], v[184:187], v[70:73]
	v_mfma_f32_16x16x32_bf16 v[66:69], v[228:231], v[184:187], v[66:69]
	v_mfma_f32_16x16x32_bf16 v[118:121], v[224:227], v[164:167], v[118:121]
	v_mfma_f32_16x16x32_bf16 v[114:117], v[232:235], v[164:167], v[114:117]
	v_mfma_f32_16x16x32_bf16 v[102:105], v[224:227], v[172:175], v[102:105]
	v_mfma_f32_16x16x32_bf16 v[98:101], v[232:235], v[172:175], v[98:101]
	v_mfma_f32_16x16x32_bf16 v[86:89], v[224:227], v[180:183], v[86:89]
	v_mfma_f32_16x16x32_bf16 v[82:85], v[232:235], v[180:183], v[82:85]
	v_mfma_f32_16x16x32_bf16 v[70:73], v[224:227], v[188:191], v[70:73]
	v_mfma_f32_16x16x32_bf16 v[66:69], v[232:235], v[188:191], v[66:69]
	s_setprio 0
	s_mov_b32 m0, s60
	v_lshl_add_u64 v[206:207], v[210:211], 0, s[36:37]
	s_barrier
	ds_read_b128 v[160:163], v144 offset:49152
	ds_read_b128 v[164:167], v144 offset:50176
	ds_read_b128 v[168:171], v144 offset:51200
	ds_read_b128 v[172:175], v144 offset:52224
	ds_read_b128 v[176:179], v144 offset:53248
	ds_read_b128 v[180:183], v144 offset:54272
	ds_read_b128 v[184:187], v144 offset:55296
	ds_read_b128 v[188:191], v144 offset:56320
	global_load_lds_dwordx4 v[206:207], off
	v_lshl_add_u64 v[206:207], v[212:213], 0, s[36:37]
	s_mov_b32 m0, s61
	s_nop 0
	global_load_lds_dwordx4 v[206:207], off
	s_barrier
; __device__ __forceinline__ unsigned cvt_pk_bf16(float lo, float hi) { const f32x2_t v = {lo, hi}; const bf16x2_t b = __builtin_convertvector(v, bf16x2_t); return __builtin_bit_cast(unsigned, b); }
; #define PG8_STAGE(bufoff, gbase, voff) do { _Pragma("unroll") for (int _i = 0; _i < 2; ++_i) \
;         __builtin_amdgcn_global_load_lds((const unsigned*)((const char*)(gbase) + (voff)[_i]), (LAS unsigned*)(lds + (bufoff) + ldsw + _i * 8192), 16, 0, 0); } while (0)
;     __device__ __forceinline__ void operator()(const f32x4 (&acc)[2][2][4][2], const Unit& u, int wr, int wc, int fr, int fq) const {
;         const int row0 = u.pm * BM + wr * 64 + fr, col0 = u.pn * BM + wc * 32 + 4 * fq;
; #pragma unroll
;         for (int ai = 0; ai < 2; ++ai)
; #pragma unroll
;             for (int m = 0; m < 4; ++m) { const size_t row = row0 + ai * HALF + m * 16; float* xr = X + row * 1024 + col0; bf16_t* br = XB + row * 1024 + col0; float ss = 0.f;
; #pragma unroll
;                 for (int bj = 0; bj < 2; ++bj)
; #pragma unroll
;                     for (int n = 0; n < 2; ++n) { f32x4 x = *(const f32x4*)(xr + bj * HALF + n * 16); x += acc[ai][bj][m][n]; *(f32x4*)(xr + bj * HALF + n * 16) = x;
;                         u32x2 w; w.x = cvt_pk_bf16(x[0], x[1]); w.y = cvt_pk_bf16(x[2], x[3]); *(u32x2*)(br + bj * HALF + n * 16) = w;
;                         ss += (x[0] * x[0] + x[1] * x[1]) + (x[2] * x[2] + x[3] * x[3]); }
;                 ss += __shfl_xor(ss, 16); ss += __shfl_xor(ss, 32);
;                 if (fq == 0) SS[row * 16 + u.pn * 4 + wc] = ss;
; template <class Epi>
; __device__ __forceinline__ void gemm_phase(LAS unsigned char* lds, const Gemm g, const StaticOrder& S, const Epi& E) {
;     ...
;             PG8_WAIT_V(6); PG8_BAR; PG8_MMA(1, 1, At, B1); PG8_BAR;
;             PG8_LDB(B0, 1, 0); PG8_SCHED; PG8_LDA(At, 1, 0); PG8_STAGE(PG8_SA(0, 1), a2 + hstep, voffA);
;             PG8_WAIT_L(8); PG8_BAR; PG8_WAIT_L(0); PG8_MMA(0, 0, At, B0); PG8_BAR; PG8_SCHED;
;             PG8_LDB(B1, 1, 1); PG8_STAGE(PG8_SB(1, 0), b3, voffB);
;             PG8_BAR; PG8_WAIT_L(0); PG8_MMA(0, 1, At, B1); PG8_BAR;
;             PG8_LDA(At, 1, 1); PG8_STAGE(PG8_SA(1, 0), a3, voffA);
;             PG8_BAR; PG8_WAIT_L(0); PG8_MMA(1, 0, At, B0); PG8_BAR; PG8_SCHED;
;             PG8_STAGE(PG8_SB(1, 1), b3 + hstep, voffB);
;             PG8_WAIT_V(6); PG8_BAR; PG8_MMA(1, 1, At, B1); PG8_BAR;
	s_waitcnt lgkmcnt(0)
	s_setprio 1
	s_waitcnt lgkmcnt(0)
	v_mfma_f32_16x16x32_bf16 v[62:65], v[138:141], v[160:163], v[62:65]
	v_mfma_f32_16x16x32_bf16 v[58:61], v[150:153], v[160:163], v[58:61]
	v_mfma_f32_16x16x32_bf16 v[46:49], v[138:141], v[168:171], v[46:49]
	v_mfma_f32_16x16x32_bf16 v[42:45], v[150:153], v[168:171], v[42:45]
	v_mfma_f32_16x16x32_bf16 v[30:33], v[138:141], v[176:179], v[30:33]
	v_mfma_f32_16x16x32_bf16 v[26:29], v[150:153], v[176:179], v[26:29]
	v_mfma_f32_16x16x32_bf16 v[14:17], v[138:141], v[184:187], v[14:17]
	v_mfma_f32_16x16x32_bf16 v[10:13], v[150:153], v[184:187], v[10:13]
	v_mfma_f32_16x16x32_bf16 v[62:65], v[146:149], v[164:167], v[62:65]
	v_mfma_f32_16x16x32_bf16 v[58:61], v[156:159], v[164:167], v[58:61]
	v_mfma_f32_16x16x32_bf16 v[46:49], v[146:149], v[172:175], v[46:49]
	v_mfma_f32_16x16x32_bf16 v[42:45], v[156:159], v[172:175], v[42:45]
	v_mfma_f32_16x16x32_bf16 v[30:33], v[146:149], v[180:183], v[30:33]
	v_mfma_f32_16x16x32_bf16 v[26:29], v[156:159], v[180:183], v[26:29]
	v_mfma_f32_16x16x32_bf16 v[14:17], v[146:149], v[188:191], v[14:17]
	v_mfma_f32_16x16x32_bf16 v[10:13], v[156:159], v[188:191], v[10:13]
	s_setprio 0
	s_barrier
	s_add_i32 s6, s8, s55
	v_lshl_add_u64 v[138:139], v[214:215], 0, s[36:37]
	s_mov_b32 m0, s6
	s_nop 0
	global_load_lds_dwordx4 v[138:139], off
	v_lshl_add_u64 v[138:139], v[216:217], 0, s[36:37]
	s_add_i32 m0, s6, 0x2000
	s_nop 0
	global_load_lds_dwordx4 v[138:139], off
	s_waitcnt vmcnt(6)
	s_barrier
	s_setprio 1
	v_mfma_f32_16x16x32_bf16 v[54:57], v[192:195], v[160:163], v[54:57]
	v_mfma_f32_16x16x32_bf16 v[50:53], v[228:231], v[160:163], v[50:53]
	v_mfma_f32_16x16x32_bf16 v[38:41], v[192:195], v[168:171], v[38:41]
	v_mfma_f32_16x16x32_bf16 v[34:37], v[228:231], v[168:171], v[34:37]
	v_mfma_f32_16x16x32_bf16 v[22:25], v[192:195], v[176:179], v[22:25]
	v_mfma_f32_16x16x32_bf16 v[18:21], v[228:231], v[176:179], v[18:21]
	v_mfma_f32_16x16x32_bf16 v[6:9], v[192:195], v[184:187], v[6:9]
	v_mfma_f32_16x16x32_bf16 v[2:5], v[228:231], v[184:187], v[2:5]
	v_mfma_f32_16x16x32_bf16 v[54:57], v[224:227], v[164:167], v[54:57]
	v_mfma_f32_16x16x32_bf16 v[50:53], v[232:235], v[164:167], v[50:53]
	v_mfma_f32_16x16x32_bf16 v[38:41], v[224:227], v[172:175], v[38:41]
	v_mfma_f32_16x16x32_bf16 v[34:37], v[232:235], v[172:175], v[34:37]
	v_mfma_f32_16x16x32_bf16 v[22:25], v[224:227], v[180:183], v[22:25]
	v_mfma_f32_16x16x32_bf16 v[18:21], v[232:235], v[180:183], v[18:21]
	v_mfma_f32_16x16x32_bf16 v[6:9], v[224:227], v[188:191], v[6:9]
	v_mfma_f32_16x16x32_bf16 v[2:5], v[232:235], v[188:191], v[2:5]
	s_setprio 0
	s_add_u32 s44, s44, 0x100
	s_addc_u32 s45, s45, 0
	s_add_u32 s4, s4, 0x100
	s_addc_u32 s5, s5, 0
	s_cmp_ge_u32 s7, s63
	s_mov_b32 s6, s7
	s_barrier
	s_cbranch_scc0 .LBB0_674
	v_lshl_add_u32 v140, s68, 8, v1
	v_ashrrev_i32_e32 v141, 31, v140
	v_lshl_or_b32 v138, s28, 8, v143
	v_lshlrev_b64 v[146:147], 12, v[140:141]
	v_ashrrev_i32_e32 v139, 31, v138
	v_lshl_add_u64 v[146:147], s[88:89], 0, v[146:147]
	v_lshl_add_u64 v[156:157], v[138:139], 2, v[146:147]
	global_load_dwordx4 v[146:149], v[156:157], off
	global_load_dwordx4 v[160:163], v[156:157], off offset:64
	global_load_dwordx4 v[164:167], v[156:157], off offset:512
	global_load_dwordx4 v[168:171], v[156:157], off offset:576
	v_readlane_b32 s2, v251, 20
	v_lshlrev_b64 v[150:151], 11, v[140:141]
	v_readlane_b32 s3, v251, 21
	v_xor_b32_e32 v145, 32, v200
	s_lshl_b32 s44, s28, 2
	v_lshl_add_u64 v[150:151], s[2:3], 0, v[150:151]
	v_lshl_add_u64 v[158:159], v[138:139], 1, v[150:151]
	s_ashr_i32 s45, s44, 31
	s_waitcnt vmcnt(3)
	v_pk_add_f32 v[128:129], v[128:129], v[148:149]
	v_pk_add_f32 v[126:127], v[126:127], v[146:147]
	v_cvt_pk_bf16_f32 v147, v128, v129
	v_cvt_pk_bf16_f32 v146, v126, v127
	global_store_dwordx4 v[156:157], v[126:129], off
	global_store_dwordx2 v[158:159], v[146:147], off
	s_waitcnt vmcnt(4)
	v_mov_b32_e32 v146, v160
	v_mov_b32_e32 v147, v161
	v_mov_b32_e32 v148, v162
	v_mov_b32_e32 v149, v163
	v_pk_add_f32 v[124:125], v[124:125], v[148:149]
	v_pk_add_f32 v[122:123], v[122:123], v[146:147]
	v_cvt_pk_bf16_f32 v147, v124, v125
	v_cvt_pk_bf16_f32 v146, v122, v123
	global_store_dwordx4 v[156:157], v[122:125], off offset:64
	global_store_dwordx2 v[158:159], v[146:147], off offset:32
	s_waitcnt vmcnt(5)
	v_mov_b32_e32 v146, v164
	v_mov_b32_e32 v147, v165
	v_mov_b32_e32 v148, v166
	v_mov_b32_e32 v149, v167
	v_pk_add_f32 v[148:149], v[120:121], v[148:149]
	v_pk_add_f32 v[146:147], v[118:119], v[146:147]
	v_cvt_pk_bf16_f32 v119, v148, v149
	v_cvt_pk_bf16_f32 v118, v146, v147
	global_store_dwordx4 v[156:157], v[146:149], off offset:512
	global_store_dwordx2 v[158:159], v[118:119], off offset:256
	v_mul_f32_e32 v120, v127, v127
	v_mul_f32_e32 v121, v129, v129
	v_fmac_f32_e32 v120, v126, v126
	v_fmac_f32_e32 v121, v128, v128
	v_add_f32_e32 v120, v120, v121
	v_mul_f32_e32 v121, v123, v123
	v_mul_f32_e32 v123, v125, v125
	v_fmac_f32_e32 v121, v122, v122
	v_fmac_f32_e32 v123, v124, v124
	v_add_f32_e32 v121, v121, v123
	v_add_f32_e32 v120, v120, v121
	v_mul_f32_e32 v121, v147, v147
	v_mul_f32_e32 v122, v149, v149
	v_fmac_f32_e32 v121, v146, v146
	v_fmac_f32_e32 v122, v148, v148
	v_add_f32_e32 v121, v121, v122
	v_and_b32_e32 v119, 64, v200
	v_add_f32_e32 v124, v120, v121
	v_xor_b32_e32 v118, 16, v200
	v_add_u32_e32 v119, 64, v119
	v_cmp_lt_i32_e32 vcc, v118, v119
	s_waitcnt vmcnt(6)
	v_mov_b32_e32 v150, v168
	v_mov_b32_e32 v151, v169
	v_mov_b32_e32 v152, v170
	v_mov_b32_e32 v153, v171
	v_pk_add_f32 v[122:123], v[116:117], v[152:153]
	v_pk_add_f32 v[120:121], v[114:115], v[150:151]
	v_mul_f32_e32 v115, v123, v123
	v_mul_f32_e32 v114, v121, v121
	v_fmac_f32_e32 v114, v120, v120
	v_fmac_f32_e32 v115, v122, v122
	v_cndmask_b32_e32 v118, v200, v118, vcc
	v_add_f32_e32 v114, v114, v115
	v_lshlrev_b32_e32 v118, 2, v118
	v_add_f32_e32 v114, v124, v114
	ds_bpermute_b32 v115, v118, v114
	v_cmp_lt_i32_e32 vcc, v145, v119
	global_store_dwordx4 v[156:157], v[120:123], off offset:576
	s_waitcnt lgkmcnt(0)
	v_add_f32_e32 v114, v114, v115
	v_cndmask_b32_e32 v116, v200, v145, vcc
	v_lshlrev_b32_e32 v116, 2, v116
	ds_bpermute_b32 v115, v116, v114
	v_cvt_pk_bf16_f32 v120, v120, v121
	v_cvt_pk_bf16_f32 v121, v122, v123
	global_store_dwordx2 v[158:159], v[120:121], off offset:288
	s_and_saveexec_b64 s[46:47], s[40:41]
	s_cbranch_execz .LBB0_677
	v_readlane_b32 s2, v251, 6
	v_lshlrev_b64 v[120:121], 6, v[140:141]
	v_readlane_b32 s3, v251, 7
	s_lshl_b32 s28, s62, 2
	s_waitcnt lgkmcnt(0)
	v_add_f32_e32 v114, v114, v115
	v_lshl_add_u64 v[120:121], s[2:3], 0, v[120:121]
	v_lshl_add_u64 v[120:121], s[44:45], 2, v[120:121]
	v_lshl_add_u64 v[120:121], v[120:121], 0, s[28:29]
	global_store_dword v[120:121], v114, off
; __device__ __forceinline__ unsigned cvt_pk_bf16(float lo, float hi) { const f32x2_t v = {lo, hi}; const bf16x2_t b = __builtin_convertvector(v, bf16x2_t); return __builtin_bit_cast(unsigned, b); }
;     __device__ __forceinline__ void operator()(const f32x4 (&acc)[2][2][4][2], const Unit& u, int wr, int wc, int fr, int fq) const {
;     ...
;             for (int m = 0; m < 4; ++m) { const size_t row = row0 + ai * HALF + m * 16; float* xr = X + row * 1024 + col0; bf16_t* br = XB + row * 1024 + col0; float ss = 0.f;
; #pragma unroll
;                 for (int bj = 0; bj < 2; ++bj)
; #pragma unroll
;                     for (int n = 0; n < 2; ++n) { f32x4 x = *(const f32x4*)(xr + bj * HALF + n * 16); x += acc[ai][bj][m][n]; *(f32x4*)(xr + bj * HALF + n * 16) = x;
;                         u32x2 w; w.x = cvt_pk_bf16(x[0], x[1]); w.y = cvt_pk_bf16(x[2], x[3]); *(u32x2*)(br + bj * HALF + n * 16) = w;
;                         ss += (x[0] * x[0] + x[1] * x[1]) + (x[2] * x[2] + x[3] * x[3]); }
;                 ss += __shfl_xor(ss, 16); ss += __shfl_xor(ss, 32);
;                 if (fq == 0) SS[row * 16 + u.pn * 4 + wc] = ss;
.LBB0_677:
	s_or_b64 exec, exec, s[46:47]
	v_or_b32_e32 v114, 16, v140
	s_waitcnt lgkmcnt(0)
	v_ashrrev_i32_e32 v115, 31, v114
	v_lshlrev_b64 v[120:121], 12, v[114:115]
	v_lshl_add_u64 v[120:121], s[88:89], 0, v[120:121]
	v_lshl_add_u64 v[124:125], v[138:139], 2, v[120:121]
	global_load_dwordx4 v[120:123], v[124:125], off
	global_load_dwordx4 v[160:163], v[124:125], off offset:64
	global_load_dwordx4 v[164:167], v[124:125], off offset:512
	global_load_dwordx4 v[168:171], v[124:125], off offset:576
	v_readlane_b32 s2, v251, 20
	v_lshlrev_b64 v[126:127], 11, v[114:115]
	v_readlane_b32 s3, v251, 21
	s_waitcnt vmcnt(3)
	v_pk_add_f32 v[112:113], v[112:113], v[122:123]
	v_lshl_add_u64 v[126:127], s[2:3], 0, v[126:127]
	v_pk_add_f32 v[110:111], v[110:111], v[120:121]
	v_lshl_add_u64 v[126:127], v[138:139], 1, v[126:127]
	v_cvt_pk_bf16_f32 v120, v110, v111
	v_cvt_pk_bf16_f32 v121, v112, v113
	global_store_dwordx4 v[124:125], v[110:113], off
	global_store_dwordx2 v[126:127], v[120:121], off
	v_mul_f32_e32 v111, v111, v111
	v_mul_f32_e32 v113, v113, v113
	v_fmac_f32_e32 v111, v110, v110
	v_fmac_f32_e32 v113, v112, v112
	v_add_f32_e32 v110, v111, v113
	s_waitcnt vmcnt(4)
	v_mov_b32_e32 v120, v160
	v_mov_b32_e32 v121, v161
	v_mov_b32_e32 v122, v162
	v_mov_b32_e32 v123, v163
	v_pk_add_f32 v[108:109], v[108:109], v[122:123]
	v_pk_add_f32 v[106:107], v[106:107], v[120:121]
	v_cvt_pk_bf16_f32 v121, v108, v109
	v_cvt_pk_bf16_f32 v120, v106, v107
	global_store_dwordx4 v[124:125], v[106:109], off offset:64
	global_store_dwordx2 v[126:127], v[120:121], off offset:32
	v_mul_f32_e32 v107, v107, v107
	v_mul_f32_e32 v109, v109, v109
	v_fmac_f32_e32 v107, v106, v106
	v_fmac_f32_e32 v109, v108, v108
	v_add_f32_e32 v106, v107, v109
	v_add_f32_e32 v106, v110, v106
	s_waitcnt vmcnt(5)
	v_mov_b32_e32 v120, v164
	v_mov_b32_e32 v121, v165
	v_mov_b32_e32 v122, v166
	v_mov_b32_e32 v123, v167
	v_pk_add_f32 v[104:105], v[104:105], v[122:123]
	v_pk_add_f32 v[102:103], v[102:103], v[120:121]
	v_cvt_pk_bf16_f32 v121, v104, v105
	v_cvt_pk_bf16_f32 v120, v102, v103
	global_store_dwordx4 v[124:125], v[102:105], off offset:512
	global_store_dwordx2 v[126:127], v[120:121], off offset:256
	v_mul_f32_e32 v103, v103, v103
	v_mul_f32_e32 v105, v105, v105
	v_fmac_f32_e32 v103, v102, v102
	v_fmac_f32_e32 v105, v104, v104
	v_add_f32_e32 v102, v103, v105
	v_add_f32_e32 v104, v106, v102
	s_waitcnt vmcnt(6)
	v_mov_b32_e32 v120, v168
	v_mov_b32_e32 v121, v169
	v_mov_b32_e32 v122, v170
	v_mov_b32_e32 v123, v171
	v_pk_add_f32 v[102:103], v[100:101], v[122:123]
	v_pk_add_f32 v[100:101], v[98:99], v[120:121]
	v_mul_f32_e32 v99, v103, v103
	v_mul_f32_e32 v98, v101, v101
	v_fmac_f32_e32 v98, v100, v100
	v_fmac_f32_e32 v99, v102, v102
	v_add_f32_e32 v98, v98, v99
	v_add_f32_e32 v98, v104, v98
	ds_bpermute_b32 v99, v118, v98
	global_store_dwordx4 v[124:125], v[100:103], off offset:576
	s_waitcnt lgkmcnt(0)
	v_add_f32_e32 v98, v98, v99
	ds_bpermute_b32 v99, v116, v98
	v_cvt_pk_bf16_f32 v100, v100, v101
	v_cvt_pk_bf16_f32 v101, v102, v103
	global_store_dwordx2 v[126:127], v[100:101], off offset:288
	s_and_saveexec_b64 s[46:47], s[40:41]
	s_cbranch_execz .LBB0_679
	v_readlane_b32 s2, v251, 6
	v_lshlrev_b64 v[100:101], 6, v[114:115]
	v_readlane_b32 s3, v251, 7
	s_lshl_b32 s28, s62, 2
	s_waitcnt lgkmcnt(0)
	v_add_f32_e32 v98, v98, v99
	v_lshl_add_u64 v[100:101], s[2:3], 0, v[100:101]
	v_lshl_add_u64 v[100:101], s[44:45], 2, v[100:101]
	v_lshl_add_u64 v[100:101], v[100:101], 0, s[28:29]
	global_store_dword v[100:101], v98, off
.LBB0_679:
	s_or_b64 exec, exec, s[46:47]
	v_or_b32_e32 v98, 32, v140
	s_waitcnt lgkmcnt(0)
	v_ashrrev_i32_e32 v99, 31, v98
	v_lshlrev_b64 v[100:101], 12, v[98:99]
	v_lshl_add_u64 v[100:101], s[88:89], 0, v[100:101]
	v_lshl_add_u64 v[104:105], v[138:139], 2, v[100:101]
	global_load_dwordx4 v[100:103], v[104:105], off
	global_load_dwordx4 v[160:163], v[104:105], off offset:64
	global_load_dwordx4 v[164:167], v[104:105], off offset:512
	global_load_dwordx4 v[168:171], v[104:105], off offset:576
	v_readlane_b32 s2, v251, 20
	v_lshlrev_b64 v[106:107], 11, v[98:99]
	v_readlane_b32 s3, v251, 21
	s_waitcnt vmcnt(3)
	v_pk_add_f32 v[96:97], v[96:97], v[102:103]
	v_lshl_add_u64 v[106:107], s[2:3], 0, v[106:107]
	v_pk_add_f32 v[94:95], v[94:95], v[100:101]
	v_lshl_add_u64 v[106:107], v[138:139], 1, v[106:107]
	v_cvt_pk_bf16_f32 v100, v94, v95
	v_cvt_pk_bf16_f32 v101, v96, v97
	global_store_dwordx4 v[104:105], v[94:97], off
	global_store_dwordx2 v[106:107], v[100:101], off
	v_mul_f32_e32 v95, v95, v95
	v_mul_f32_e32 v97, v97, v97
	v_fmac_f32_e32 v95, v94, v94
	v_fmac_f32_e32 v97, v96, v96
	v_add_f32_e32 v94, v95, v97
	s_waitcnt vmcnt(4)
	v_mov_b32_e32 v100, v160
	v_mov_b32_e32 v101, v161
	v_mov_b32_e32 v102, v162
	v_mov_b32_e32 v103, v163
	v_pk_add_f32 v[92:93], v[92:93], v[102:103]
	v_pk_add_f32 v[90:91], v[90:91], v[100:101]
	v_cvt_pk_bf16_f32 v101, v92, v93
	v_cvt_pk_bf16_f32 v100, v90, v91
	global_store_dwordx4 v[104:105], v[90:93], off offset:64
	global_store_dwordx2 v[106:107], v[100:101], off offset:32
	v_mul_f32_e32 v91, v91, v91
	v_mul_f32_e32 v93, v93, v93
	v_fmac_f32_e32 v91, v90, v90
	v_fmac_f32_e32 v93, v92, v92
	v_add_f32_e32 v90, v91, v93
	v_add_f32_e32 v90, v94, v90
	s_waitcnt vmcnt(5)
	v_mov_b32_e32 v100, v164
	v_mov_b32_e32 v101, v165
	v_mov_b32_e32 v102, v166
	v_mov_b32_e32 v103, v167
	v_pk_add_f32 v[88:89], v[88:89], v[102:103]
	v_pk_add_f32 v[86:87], v[86:87], v[100:101]
	v_cvt_pk_bf16_f32 v101, v88, v89
	v_cvt_pk_bf16_f32 v100, v86, v87
	global_store_dwordx4 v[104:105], v[86:89], off offset:512
	global_store_dwordx2 v[106:107], v[100:101], off offset:256
	v_mul_f32_e32 v87, v87, v87
	v_mul_f32_e32 v89, v89, v89
	v_fmac_f32_e32 v87, v86, v86
	v_fmac_f32_e32 v89, v88, v88
	v_add_f32_e32 v86, v87, v89
	v_add_f32_e32 v88, v90, v86
	s_waitcnt vmcnt(6)
	v_mov_b32_e32 v100, v168
	v_mov_b32_e32 v101, v169
	v_mov_b32_e32 v102, v170
	v_mov_b32_e32 v103, v171
	v_pk_add_f32 v[86:87], v[84:85], v[102:103]
	v_pk_add_f32 v[84:85], v[82:83], v[100:101]
	v_mul_f32_e32 v83, v87, v87
	v_mul_f32_e32 v82, v85, v85
	v_fmac_f32_e32 v82, v84, v84
	v_fmac_f32_e32 v83, v86, v86
	v_add_f32_e32 v82, v82, v83
	v_add_f32_e32 v82, v88, v82
	ds_bpermute_b32 v83, v118, v82
	global_store_dwordx4 v[104:105], v[84:87], off offset:576
	s_waitcnt lgkmcnt(0)
	v_add_f32_e32 v82, v82, v83
	ds_bpermute_b32 v83, v116, v82
	v_cvt_pk_bf16_f32 v84, v84, v85
	v_cvt_pk_bf16_f32 v85, v86, v87
	global_store_dwordx2 v[106:107], v[84:85], off offset:288
	s_and_saveexec_b64 s[46:47], s[40:41]
	s_cbranch_execz .LBB0_681
	v_readlane_b32 s2, v251, 6
	v_lshlrev_b64 v[84:85], 6, v[98:99]
	v_readlane_b32 s3, v251, 7
	s_lshl_b32 s28, s62, 2
	s_waitcnt lgkmcnt(0)
	v_add_f32_e32 v82, v82, v83
	v_lshl_add_u64 v[84:85], s[2:3], 0, v[84:85]
	v_lshl_add_u64 v[84:85], s[44:45], 2, v[84:85]
	v_lshl_add_u64 v[84:85], v[84:85], 0, s[28:29]
	global_store_dword v[84:85], v82, off
; __device__ __forceinline__ unsigned cvt_pk_bf16(float lo, float hi) { const f32x2_t v = {lo, hi}; const bf16x2_t b = __builtin_convertvector(v, bf16x2_t); return __builtin_bit_cast(unsigned, b); }
;     __device__ __forceinline__ void operator()(const f32x4 (&acc)[2][2][4][2], const Unit& u, int wr, int wc, int fr, int fq) const {
;     ...
;             for (int m = 0; m < 4; ++m) { const size_t row = row0 + ai * HALF + m * 16; float* xr = X + row * 1024 + col0; bf16_t* br = XB + row * 1024 + col0; float ss = 0.f;
; #pragma unroll
;                 for (int bj = 0; bj < 2; ++bj)
; #pragma unroll
;                     for (int n = 0; n < 2; ++n) { f32x4 x = *(const f32x4*)(xr + bj * HALF + n * 16); x += acc[ai][bj][m][n]; *(f32x4*)(xr + bj * HALF + n * 16) = x;
;                         u32x2 w; w.x = cvt_pk_bf16(x[0], x[1]); w.y = cvt_pk_bf16(x[2], x[3]); *(u32x2*)(br + bj * HALF + n * 16) = w;
;                         ss += (x[0] * x[0] + x[1] * x[1]) + (x[2] * x[2] + x[3] * x[3]); }
;                 ss += __shfl_xor(ss, 16); ss += __shfl_xor(ss, 32);
;                 if (fq == 0) SS[row * 16 + u.pn * 4 + wc] = ss;
.LBB0_681:
	s_or_b64 exec, exec, s[46:47]
	v_or_b32_e32 v82, 48, v140
	s_waitcnt lgkmcnt(0)
	v_ashrrev_i32_e32 v83, 31, v82
	v_lshlrev_b64 v[84:85], 12, v[82:83]
	v_lshl_add_u64 v[84:85], s[88:89], 0, v[84:85]
	v_lshl_add_u64 v[88:89], v[138:139], 2, v[84:85]
	global_load_dwordx4 v[84:87], v[88:89], off
	global_load_dwordx4 v[160:163], v[88:89], off offset:64
	global_load_dwordx4 v[164:167], v[88:89], off offset:512
	global_load_dwordx4 v[168:171], v[88:89], off offset:576
	v_readlane_b32 s2, v251, 20
	v_lshlrev_b64 v[90:91], 11, v[82:83]
	v_readlane_b32 s3, v251, 21
	s_waitcnt vmcnt(3)
	v_pk_add_f32 v[80:81], v[80:81], v[86:87]
	v_lshl_add_u64 v[90:91], s[2:3], 0, v[90:91]
	v_pk_add_f32 v[78:79], v[78:79], v[84:85]
	v_lshl_add_u64 v[90:91], v[138:139], 1, v[90:91]
	v_cvt_pk_bf16_f32 v84, v78, v79
	v_cvt_pk_bf16_f32 v85, v80, v81
	global_store_dwordx4 v[88:89], v[78:81], off
	global_store_dwordx2 v[90:91], v[84:85], off
	v_mul_f32_e32 v79, v79, v79
	v_mul_f32_e32 v81, v81, v81
	v_fmac_f32_e32 v79, v78, v78
	v_fmac_f32_e32 v81, v80, v80
	v_add_f32_e32 v78, v79, v81
	s_waitcnt vmcnt(4)
	v_mov_b32_e32 v84, v160
	v_mov_b32_e32 v85, v161
	v_mov_b32_e32 v86, v162
	v_mov_b32_e32 v87, v163
	v_pk_add_f32 v[76:77], v[76:77], v[86:87]
	v_pk_add_f32 v[74:75], v[74:75], v[84:85]
	v_cvt_pk_bf16_f32 v85, v76, v77
	v_cvt_pk_bf16_f32 v84, v74, v75
	global_store_dwordx4 v[88:89], v[74:77], off offset:64
	global_store_dwordx2 v[90:91], v[84:85], off offset:32
	v_mul_f32_e32 v75, v75, v75
	v_mul_f32_e32 v77, v77, v77
	v_fmac_f32_e32 v75, v74, v74
	v_fmac_f32_e32 v77, v76, v76
	v_add_f32_e32 v74, v75, v77
	v_add_f32_e32 v74, v78, v74
	s_waitcnt vmcnt(5)
	v_mov_b32_e32 v84, v164
	v_mov_b32_e32 v85, v165
	v_mov_b32_e32 v86, v166
	v_mov_b32_e32 v87, v167
	v_pk_add_f32 v[72:73], v[72:73], v[86:87]
	v_pk_add_f32 v[70:71], v[70:71], v[84:85]
	v_cvt_pk_bf16_f32 v85, v72, v73
	v_cvt_pk_bf16_f32 v84, v70, v71
	global_store_dwordx4 v[88:89], v[70:73], off offset:512
	global_store_dwordx2 v[90:91], v[84:85], off offset:256
	v_mul_f32_e32 v71, v71, v71
	v_mul_f32_e32 v73, v73, v73
	v_fmac_f32_e32 v71, v70, v70
	v_fmac_f32_e32 v73, v72, v72
	v_add_f32_e32 v70, v71, v73
	v_add_f32_e32 v72, v74, v70
	s_waitcnt vmcnt(6)
	v_mov_b32_e32 v84, v168
	v_mov_b32_e32 v85, v169
	v_mov_b32_e32 v86, v170
	v_mov_b32_e32 v87, v171
	v_pk_add_f32 v[70:71], v[68:69], v[86:87]
	v_pk_add_f32 v[68:69], v[66:67], v[84:85]
	v_mul_f32_e32 v67, v71, v71
	v_mul_f32_e32 v66, v69, v69
	v_fmac_f32_e32 v66, v68, v68
	v_fmac_f32_e32 v67, v70, v70
	v_add_f32_e32 v66, v66, v67
	v_add_f32_e32 v66, v72, v66
	ds_bpermute_b32 v67, v118, v66
	global_store_dwordx4 v[88:89], v[68:71], off offset:576
	s_waitcnt lgkmcnt(0)
	v_add_f32_e32 v66, v66, v67
	ds_bpermute_b32 v67, v116, v66
	v_cvt_pk_bf16_f32 v68, v68, v69
	v_cvt_pk_bf16_f32 v69, v70, v71
	global_store_dwordx2 v[90:91], v[68:69], off offset:288
	s_and_saveexec_b64 s[46:47], s[40:41]
	s_cbranch_execz .LBB0_683
	v_readlane_b32 s2, v251, 6
	v_lshlrev_b64 v[68:69], 6, v[82:83]
	v_readlane_b32 s3, v251, 7
	s_lshl_b32 s28, s62, 2
	s_waitcnt lgkmcnt(0)
	v_add_f32_e32 v66, v66, v67
	v_lshl_add_u64 v[68:69], s[2:3], 0, v[68:69]
	v_lshl_add_u64 v[68:69], s[44:45], 2, v[68:69]
	v_lshl_add_u64 v[68:69], v[68:69], 0, s[28:29]
	global_store_dword v[68:69], v66, off
.LBB0_683:
	s_or_b64 exec, exec, s[46:47]
	v_add_u32_e32 v66, 0x80, v140
	s_waitcnt lgkmcnt(0)
	v_ashrrev_i32_e32 v67, 31, v66
	v_lshlrev_b64 v[68:69], 12, v[66:67]
	v_lshl_add_u64 v[68:69], s[88:89], 0, v[68:69]
	v_lshl_add_u64 v[72:73], v[138:139], 2, v[68:69]
	global_load_dwordx4 v[68:71], v[72:73], off
	global_load_dwordx4 v[160:163], v[72:73], off offset:64
	global_load_dwordx4 v[164:167], v[72:73], off offset:512
	global_load_dwordx4 v[168:171], v[72:73], off offset:576
	v_readlane_b32 s2, v251, 20
	v_lshlrev_b64 v[74:75], 11, v[66:67]
	v_readlane_b32 s3, v251, 21
	s_waitcnt vmcnt(3)
	v_pk_add_f32 v[64:65], v[64:65], v[70:71]
	v_lshl_add_u64 v[74:75], s[2:3], 0, v[74:75]
	v_pk_add_f32 v[62:63], v[62:63], v[68:69]
	v_lshl_add_u64 v[74:75], v[138:139], 1, v[74:75]
	v_cvt_pk_bf16_f32 v68, v62, v63
	v_cvt_pk_bf16_f32 v69, v64, v65
	global_store_dwordx4 v[72:73], v[62:65], off
	global_store_dwordx2 v[74:75], v[68:69], off
	v_mul_f32_e32 v63, v63, v63
	v_mul_f32_e32 v65, v65, v65
	v_fmac_f32_e32 v63, v62, v62
	v_fmac_f32_e32 v65, v64, v64
	v_add_f32_e32 v62, v63, v65
	s_waitcnt vmcnt(4)
	v_mov_b32_e32 v68, v160
	v_mov_b32_e32 v69, v161
	v_mov_b32_e32 v70, v162
	v_mov_b32_e32 v71, v163
	v_pk_add_f32 v[60:61], v[60:61], v[70:71]
	v_pk_add_f32 v[58:59], v[58:59], v[68:69]
	v_cvt_pk_bf16_f32 v69, v60, v61
	v_cvt_pk_bf16_f32 v68, v58, v59
	global_store_dwordx4 v[72:73], v[58:61], off offset:64
	global_store_dwordx2 v[74:75], v[68:69], off offset:32
	v_mul_f32_e32 v59, v59, v59
	v_mul_f32_e32 v61, v61, v61
	v_fmac_f32_e32 v59, v58, v58
	v_fmac_f32_e32 v61, v60, v60
	v_add_f32_e32 v58, v59, v61
	v_add_f32_e32 v58, v62, v58
	s_waitcnt vmcnt(5)
	v_mov_b32_e32 v68, v164
	v_mov_b32_e32 v69, v165
	v_mov_b32_e32 v70, v166
	v_mov_b32_e32 v71, v167
	v_pk_add_f32 v[56:57], v[56:57], v[70:71]
	v_pk_add_f32 v[54:55], v[54:55], v[68:69]
	v_cvt_pk_bf16_f32 v69, v56, v57
	v_cvt_pk_bf16_f32 v68, v54, v55
	global_store_dwordx4 v[72:73], v[54:57], off offset:512
	global_store_dwordx2 v[74:75], v[68:69], off offset:256
	v_mul_f32_e32 v55, v55, v55
	v_mul_f32_e32 v57, v57, v57
	v_fmac_f32_e32 v55, v54, v54
	v_fmac_f32_e32 v57, v56, v56
	v_add_f32_e32 v54, v55, v57
	v_add_f32_e32 v56, v58, v54
	s_waitcnt vmcnt(6)
	v_mov_b32_e32 v68, v168
	v_mov_b32_e32 v69, v169
	v_mov_b32_e32 v70, v170
	v_mov_b32_e32 v71, v171
	v_pk_add_f32 v[54:55], v[52:53], v[70:71]
	v_pk_add_f32 v[52:53], v[50:51], v[68:69]
	v_mul_f32_e32 v51, v55, v55
	v_mul_f32_e32 v50, v53, v53
	v_fmac_f32_e32 v50, v52, v52
	v_fmac_f32_e32 v51, v54, v54
	v_add_f32_e32 v50, v50, v51
	v_add_f32_e32 v50, v56, v50
	ds_bpermute_b32 v51, v118, v50
	global_store_dwordx4 v[72:73], v[52:55], off offset:576
	s_waitcnt lgkmcnt(0)
	v_add_f32_e32 v50, v50, v51
	ds_bpermute_b32 v51, v116, v50
	v_cvt_pk_bf16_f32 v52, v52, v53
	v_cvt_pk_bf16_f32 v53, v54, v55
	global_store_dwordx2 v[74:75], v[52:53], off offset:288
	s_and_saveexec_b64 s[46:47], s[40:41]
	s_cbranch_execz .LBB0_685
	v_readlane_b32 s2, v251, 6
	v_lshlrev_b64 v[52:53], 6, v[66:67]
	v_readlane_b32 s3, v251, 7
	s_lshl_b32 s28, s62, 2
	s_waitcnt lgkmcnt(0)
	v_add_f32_e32 v50, v50, v51
	v_lshl_add_u64 v[52:53], s[2:3], 0, v[52:53]
	v_lshl_add_u64 v[52:53], s[44:45], 2, v[52:53]
	v_lshl_add_u64 v[52:53], v[52:53], 0, s[28:29]
	global_store_dword v[52:53], v50, off
; __device__ __forceinline__ unsigned cvt_pk_bf16(float lo, float hi) { const f32x2_t v = {lo, hi}; const bf16x2_t b = __builtin_convertvector(v, bf16x2_t); return __builtin_bit_cast(unsigned, b); }
;     __device__ __forceinline__ void operator()(const f32x4 (&acc)[2][2][4][2], const Unit& u, int wr, int wc, int fr, int fq) const {
;     ...
;             for (int m = 0; m < 4; ++m) { const size_t row = row0 + ai * HALF + m * 16; float* xr = X + row * 1024 + col0; bf16_t* br = XB + row * 1024 + col0; float ss = 0.f;
; #pragma unroll
;                 for (int bj = 0; bj < 2; ++bj)
; #pragma unroll
;                     for (int n = 0; n < 2; ++n) { f32x4 x = *(const f32x4*)(xr + bj * HALF + n * 16); x += acc[ai][bj][m][n]; *(f32x4*)(xr + bj * HALF + n * 16) = x;
;                         u32x2 w; w.x = cvt_pk_bf16(x[0], x[1]); w.y = cvt_pk_bf16(x[2], x[3]); *(u32x2*)(br + bj * HALF + n * 16) = w;
;                         ss += (x[0] * x[0] + x[1] * x[1]) + (x[2] * x[2] + x[3] * x[3]); }
;                 ss += __shfl_xor(ss, 16); ss += __shfl_xor(ss, 32);
;                 if (fq == 0) SS[row * 16 + u.pn * 4 + wc] = ss;
.LBB0_685:
	s_or_b64 exec, exec, s[46:47]
	v_add_u32_e32 v50, 0x90, v140
	s_waitcnt lgkmcnt(0)
	v_ashrrev_i32_e32 v51, 31, v50
	v_lshlrev_b64 v[52:53], 12, v[50:51]
	v_lshl_add_u64 v[52:53], s[88:89], 0, v[52:53]
	v_lshl_add_u64 v[56:57], v[138:139], 2, v[52:53]
	global_load_dwordx4 v[52:55], v[56:57], off
	global_load_dwordx4 v[160:163], v[56:57], off offset:64
	global_load_dwordx4 v[164:167], v[56:57], off offset:512
	global_load_dwordx4 v[168:171], v[56:57], off offset:576
	v_readlane_b32 s2, v251, 20
	v_lshlrev_b64 v[58:59], 11, v[50:51]
	v_readlane_b32 s3, v251, 21
	s_waitcnt vmcnt(3)
	v_pk_add_f32 v[48:49], v[48:49], v[54:55]
	v_lshl_add_u64 v[58:59], s[2:3], 0, v[58:59]
	v_pk_add_f32 v[46:47], v[46:47], v[52:53]
	v_lshl_add_u64 v[58:59], v[138:139], 1, v[58:59]
	v_cvt_pk_bf16_f32 v52, v46, v47
	v_cvt_pk_bf16_f32 v53, v48, v49
	global_store_dwordx4 v[56:57], v[46:49], off
	global_store_dwordx2 v[58:59], v[52:53], off
	v_mul_f32_e32 v47, v47, v47
	v_mul_f32_e32 v49, v49, v49
	v_fmac_f32_e32 v47, v46, v46
	v_fmac_f32_e32 v49, v48, v48
	v_add_f32_e32 v46, v47, v49
	s_waitcnt vmcnt(4)
	v_mov_b32_e32 v52, v160
	v_mov_b32_e32 v53, v161
	v_mov_b32_e32 v54, v162
	v_mov_b32_e32 v55, v163
	v_pk_add_f32 v[44:45], v[44:45], v[54:55]
	v_pk_add_f32 v[42:43], v[42:43], v[52:53]
	v_cvt_pk_bf16_f32 v53, v44, v45
	v_cvt_pk_bf16_f32 v52, v42, v43
	global_store_dwordx4 v[56:57], v[42:45], off offset:64
	global_store_dwordx2 v[58:59], v[52:53], off offset:32
	v_mul_f32_e32 v43, v43, v43
	v_mul_f32_e32 v45, v45, v45
	v_fmac_f32_e32 v43, v42, v42
	v_fmac_f32_e32 v45, v44, v44
	v_add_f32_e32 v42, v43, v45
	v_add_f32_e32 v42, v46, v42
	s_waitcnt vmcnt(5)
	v_mov_b32_e32 v52, v164
	v_mov_b32_e32 v53, v165
	v_mov_b32_e32 v54, v166
	v_mov_b32_e32 v55, v167
	v_pk_add_f32 v[40:41], v[40:41], v[54:55]
	v_pk_add_f32 v[38:39], v[38:39], v[52:53]
	v_cvt_pk_bf16_f32 v53, v40, v41
	v_cvt_pk_bf16_f32 v52, v38, v39
	global_store_dwordx4 v[56:57], v[38:41], off offset:512
	global_store_dwordx2 v[58:59], v[52:53], off offset:256
	v_mul_f32_e32 v39, v39, v39
	v_mul_f32_e32 v41, v41, v41
	v_fmac_f32_e32 v39, v38, v38
	v_fmac_f32_e32 v41, v40, v40
	v_add_f32_e32 v38, v39, v41
	v_add_f32_e32 v40, v42, v38
	s_waitcnt vmcnt(6)
	v_mov_b32_e32 v52, v168
	v_mov_b32_e32 v53, v169
	v_mov_b32_e32 v54, v170
	v_mov_b32_e32 v55, v171
	v_pk_add_f32 v[38:39], v[36:37], v[54:55]
	v_pk_add_f32 v[36:37], v[34:35], v[52:53]
	v_mul_f32_e32 v35, v39, v39
	v_mul_f32_e32 v34, v37, v37
	v_fmac_f32_e32 v34, v36, v36
	v_fmac_f32_e32 v35, v38, v38
	v_add_f32_e32 v34, v34, v35
	v_add_f32_e32 v34, v40, v34
	ds_bpermute_b32 v35, v118, v34
	global_store_dwordx4 v[56:57], v[36:39], off offset:576
	s_waitcnt lgkmcnt(0)
	v_add_f32_e32 v34, v34, v35
	ds_bpermute_b32 v35, v116, v34
	v_cvt_pk_bf16_f32 v36, v36, v37
	v_cvt_pk_bf16_f32 v37, v38, v39
	global_store_dwordx2 v[58:59], v[36:37], off offset:288
	s_and_saveexec_b64 s[46:47], s[40:41]
	s_cbranch_execz .LBB0_687
	v_readlane_b32 s2, v251, 6
	v_lshlrev_b64 v[36:37], 6, v[50:51]
	v_readlane_b32 s3, v251, 7
	s_lshl_b32 s28, s62, 2
	s_waitcnt lgkmcnt(0)
	v_add_f32_e32 v34, v34, v35
	v_lshl_add_u64 v[36:37], s[2:3], 0, v[36:37]
	v_lshl_add_u64 v[36:37], s[44:45], 2, v[36:37]
	v_lshl_add_u64 v[36:37], v[36:37], 0, s[28:29]
	global_store_dword v[36:37], v34, off
; __device__ __forceinline__ unsigned cvt_pk_bf16(float lo, float hi) { const f32x2_t v = {lo, hi}; const bf16x2_t b = __builtin_convertvector(v, bf16x2_t); return __builtin_bit_cast(unsigned, b); }
;     __device__ __forceinline__ void operator()(const f32x4 (&acc)[2][2][4][2], const Unit& u, int wr, int wc, int fr, int fq) const {
;     ...
;             for (int m = 0; m < 4; ++m) { const size_t row = row0 + ai * HALF + m * 16; float* xr = X + row * 1024 + col0; bf16_t* br = XB + row * 1024 + col0; float ss = 0.f;
; #pragma unroll
;                 for (int bj = 0; bj < 2; ++bj)
; #pragma unroll
;                     for (int n = 0; n < 2; ++n) { f32x4 x = *(const f32x4*)(xr + bj * HALF + n * 16); x += acc[ai][bj][m][n]; *(f32x4*)(xr + bj * HALF + n * 16) = x;
;                         u32x2 w; w.x = cvt_pk_bf16(x[0], x[1]); w.y = cvt_pk_bf16(x[2], x[3]); *(u32x2*)(br + bj * HALF + n * 16) = w;
;                         ss += (x[0] * x[0] + x[1] * x[1]) + (x[2] * x[2] + x[3] * x[3]); }
;                 ss += __shfl_xor(ss, 16); ss += __shfl_xor(ss, 32);
;                 if (fq == 0) SS[row * 16 + u.pn * 4 + wc] = ss;
.LBB0_687:
	s_or_b64 exec, exec, s[46:47]
	v_add_u32_e32 v34, 0xa0, v140
	s_waitcnt lgkmcnt(0)
	v_ashrrev_i32_e32 v35, 31, v34
	v_lshlrev_b64 v[36:37], 12, v[34:35]
	v_lshl_add_u64 v[36:37], s[88:89], 0, v[36:37]
	v_lshl_add_u64 v[40:41], v[138:139], 2, v[36:37]
	global_load_dwordx4 v[36:39], v[40:41], off
	global_load_dwordx4 v[160:163], v[40:41], off offset:64
	global_load_dwordx4 v[164:167], v[40:41], off offset:512
	global_load_dwordx4 v[168:171], v[40:41], off offset:576
	v_readlane_b32 s2, v251, 20
	v_lshlrev_b64 v[42:43], 11, v[34:35]
	v_readlane_b32 s3, v251, 21
	s_waitcnt vmcnt(3)
	v_pk_add_f32 v[32:33], v[32:33], v[38:39]
	v_lshl_add_u64 v[42:43], s[2:3], 0, v[42:43]
	v_pk_add_f32 v[30:31], v[30:31], v[36:37]
	v_lshl_add_u64 v[42:43], v[138:139], 1, v[42:43]
	v_cvt_pk_bf16_f32 v36, v30, v31
	v_cvt_pk_bf16_f32 v37, v32, v33
	global_store_dwordx4 v[40:41], v[30:33], off
	global_store_dwordx2 v[42:43], v[36:37], off
	v_mul_f32_e32 v31, v31, v31
	v_mul_f32_e32 v33, v33, v33
	v_fmac_f32_e32 v31, v30, v30
	v_fmac_f32_e32 v33, v32, v32
	v_add_f32_e32 v30, v31, v33
	s_waitcnt vmcnt(4)
	v_mov_b32_e32 v36, v160
	v_mov_b32_e32 v37, v161
	v_mov_b32_e32 v38, v162
	v_mov_b32_e32 v39, v163
	v_pk_add_f32 v[28:29], v[28:29], v[38:39]
	v_pk_add_f32 v[26:27], v[26:27], v[36:37]
	v_cvt_pk_bf16_f32 v37, v28, v29
	v_cvt_pk_bf16_f32 v36, v26, v27
	global_store_dwordx4 v[40:41], v[26:29], off offset:64
	global_store_dwordx2 v[42:43], v[36:37], off offset:32
	v_mul_f32_e32 v27, v27, v27
	v_mul_f32_e32 v29, v29, v29
	v_fmac_f32_e32 v27, v26, v26
	v_fmac_f32_e32 v29, v28, v28
	v_add_f32_e32 v26, v27, v29
	v_add_f32_e32 v26, v30, v26
	s_waitcnt vmcnt(5)
	v_mov_b32_e32 v36, v164
	v_mov_b32_e32 v37, v165
	v_mov_b32_e32 v38, v166
	v_mov_b32_e32 v39, v167
	v_pk_add_f32 v[24:25], v[24:25], v[38:39]
	v_pk_add_f32 v[22:23], v[22:23], v[36:37]
	v_cvt_pk_bf16_f32 v37, v24, v25
	v_cvt_pk_bf16_f32 v36, v22, v23
	global_store_dwordx4 v[40:41], v[22:25], off offset:512
	global_store_dwordx2 v[42:43], v[36:37], off offset:256
	v_mul_f32_e32 v23, v23, v23
	v_mul_f32_e32 v25, v25, v25
	v_fmac_f32_e32 v23, v22, v22
	v_fmac_f32_e32 v25, v24, v24
	v_add_f32_e32 v22, v23, v25
	v_add_f32_e32 v24, v26, v22
	s_waitcnt vmcnt(6)
	v_mov_b32_e32 v36, v168
	v_mov_b32_e32 v37, v169
	v_mov_b32_e32 v38, v170
	v_mov_b32_e32 v39, v171
	v_pk_add_f32 v[22:23], v[20:21], v[38:39]
	v_pk_add_f32 v[20:21], v[18:19], v[36:37]
	v_mul_f32_e32 v19, v23, v23
	v_mul_f32_e32 v18, v21, v21
	v_fmac_f32_e32 v18, v20, v20
	v_fmac_f32_e32 v19, v22, v22
	v_add_f32_e32 v18, v18, v19
	v_add_f32_e32 v18, v24, v18
	ds_bpermute_b32 v19, v118, v18
	global_store_dwordx4 v[40:41], v[20:23], off offset:576
	s_waitcnt lgkmcnt(0)
	v_add_f32_e32 v18, v18, v19
	ds_bpermute_b32 v19, v116, v18
	v_cvt_pk_bf16_f32 v20, v20, v21
	v_cvt_pk_bf16_f32 v21, v22, v23
	global_store_dwordx2 v[42:43], v[20:21], off offset:288
	s_and_saveexec_b64 s[46:47], s[40:41]
	s_cbranch_execz .LBB0_689
	v_readlane_b32 s2, v251, 6
	v_lshlrev_b64 v[20:21], 6, v[34:35]
	v_readlane_b32 s3, v251, 7
	s_lshl_b32 s28, s62, 2
	s_waitcnt lgkmcnt(0)
	v_add_f32_e32 v18, v18, v19
	v_lshl_add_u64 v[20:21], s[2:3], 0, v[20:21]
	v_lshl_add_u64 v[20:21], s[44:45], 2, v[20:21]
	v_lshl_add_u64 v[20:21], v[20:21], 0, s[28:29]
	global_store_dword v[20:21], v18, off
.LBB0_689:
	s_or_b64 exec, exec, s[46:47]
	v_add_u32_e32 v18, 0xb0, v140
	s_waitcnt lgkmcnt(0)
	v_ashrrev_i32_e32 v19, 31, v18
	v_lshlrev_b64 v[20:21], 12, v[18:19]
	v_lshl_add_u64 v[20:21], s[88:89], 0, v[20:21]
	v_readlane_b32 s2, v251, 20
	v_lshl_add_u64 v[24:25], v[138:139], 2, v[20:21]
	v_lshlrev_b64 v[20:21], 11, v[18:19]
	v_readlane_b32 s3, v251, 21
	s_nop 1
	v_lshl_add_u64 v[20:21], s[2:3], 0, v[20:21]
	v_lshl_add_u64 v[26:27], v[138:139], 1, v[20:21]
	global_load_dwordx4 v[20:23], v[24:25], off
	global_load_dwordx4 v[160:163], v[24:25], off offset:64
	global_load_dwordx4 v[164:167], v[24:25], off offset:512
	global_load_dwordx4 v[168:171], v[24:25], off offset:576
	s_waitcnt vmcnt(3)
	v_pk_add_f32 v[16:17], v[16:17], v[22:23]
	v_pk_add_f32 v[14:15], v[14:15], v[20:21]
	global_store_dwordx4 v[24:25], v[14:17], off
	v_cvt_pk_bf16_f32 v20, v14, v15
	v_cvt_pk_bf16_f32 v21, v16, v17
	v_mul_f32_e32 v15, v15, v15
	v_fmac_f32_e32 v15, v14, v14
	v_mul_f32_e32 v14, v17, v17
	global_store_dwordx2 v[26:27], v[20:21], off
	v_fmac_f32_e32 v14, v16, v16
	v_add_f32_e32 v20, v15, v14
	s_waitcnt vmcnt(4)
	v_mov_b32_e32 v14, v160
	v_mov_b32_e32 v15, v161
	v_mov_b32_e32 v16, v162
	v_mov_b32_e32 v17, v163
	v_pk_add_f32 v[12:13], v[12:13], v[16:17]
	v_pk_add_f32 v[10:11], v[10:11], v[14:15]
	global_store_dwordx4 v[24:25], v[10:13], off offset:64
	v_cvt_pk_bf16_f32 v14, v10, v11
	v_cvt_pk_bf16_f32 v15, v12, v13
	v_mul_f32_e32 v11, v11, v11
	v_fmac_f32_e32 v11, v10, v10
	v_mul_f32_e32 v10, v13, v13
	v_fmac_f32_e32 v10, v12, v12
	global_store_dwordx2 v[26:27], v[14:15], off offset:32
	v_add_f32_e32 v10, v11, v10
	v_add_f32_e32 v14, v20, v10
	s_waitcnt vmcnt(5)
	v_mov_b32_e32 v10, v164
	v_mov_b32_e32 v11, v165
	v_mov_b32_e32 v12, v166
	v_mov_b32_e32 v13, v167
	v_pk_add_f32 v[8:9], v[8:9], v[12:13]
	v_pk_add_f32 v[6:7], v[6:7], v[10:11]
	global_store_dwordx4 v[24:25], v[6:9], off offset:512
	v_cvt_pk_bf16_f32 v10, v6, v7
	v_cvt_pk_bf16_f32 v11, v8, v9
	v_mul_f32_e32 v7, v7, v7
	v_fmac_f32_e32 v7, v6, v6
	v_mul_f32_e32 v6, v9, v9
	v_fmac_f32_e32 v6, v8, v8
	global_store_dwordx2 v[26:27], v[10:11], off offset:256
	v_add_f32_e32 v6, v7, v6
	v_add_f32_e32 v10, v14, v6
	s_waitcnt vmcnt(6)
	v_mov_b32_e32 v6, v168
	v_mov_b32_e32 v7, v169
	v_mov_b32_e32 v8, v170
	v_mov_b32_e32 v9, v171
	v_pk_add_f32 v[4:5], v[4:5], v[8:9]
	v_pk_add_f32 v[2:3], v[2:3], v[6:7]
	global_store_dwordx4 v[24:25], v[2:5], off offset:576
	v_cvt_pk_bf16_f32 v6, v2, v3
	v_cvt_pk_bf16_f32 v7, v4, v5
	v_mul_f32_e32 v3, v3, v3
	v_fmac_f32_e32 v3, v2, v2
	v_mul_f32_e32 v2, v5, v5
	v_fmac_f32_e32 v2, v4, v4
	v_add_f32_e32 v2, v3, v2
	v_add_f32_e32 v2, v10, v2
	ds_bpermute_b32 v3, v118, v2
	global_store_dwordx2 v[26:27], v[6:7], off offset:288
	s_waitcnt lgkmcnt(0)
	v_add_f32_e32 v2, v2, v3
	ds_bpermute_b32 v3, v116, v2
	s_and_saveexec_b64 s[46:47], s[40:41]
	s_cbranch_execz .LBB0_662
	v_readlane_b32 s2, v251, 6
	v_lshlrev_b64 v[4:5], 6, v[18:19]
	v_readlane_b32 s3, v251, 7
	s_lshl_b32 s28, s62, 2
	s_waitcnt lgkmcnt(0)
	v_add_f32_e32 v2, v2, v3
	v_lshl_add_u64 v[4:5], s[2:3], 0, v[4:5]
	v_lshl_add_u64 v[4:5], s[44:45], 2, v[4:5]
	v_lshl_add_u64 v[4:5], v[4:5], 0, s[28:29]
	global_store_dword v[4:5], v2, off
	s_branch .LBB0_662
